# PROJA epilogue path fetches 8 steps of gate rows per batch (2 exposed round trips per unit instead of 4), stacked on the previous best
# baseline (speedup 1.0000x reference)
; DI float bf_lo(unsigned u) { return __uint_as_float(u << 16); }
; DI float bf_hi(unsigned u) { return __uint_as_float(u & 0xffff0000u); }
; #define EPI_ROWS for (int ai = 0; ai < 2; ++ai) for (int m = 0; m < 4; ++m, ({ asm volatile("" ::: "memory"); }))
; DI void store_bf8(bf16_t* p, f32x4 a, f32x4 b) { u32x4 w; w.x = pk2(a[0], a[1]); w.y = pk2(a[2], a[3]); w.z = pk2(b[0], b[1]); w.w = pk2(b[2], b[3]); *(u32x4*)p = w; }
; DI void gemm_run(const GemmDesc& d, char* lds) {
;     ...
;         case E_PROJA: case E_PROJB: {
;             const int goff = d.epi == E_PROJA ? 0 : 1024, c8 = bcol + wc * 32 + fq * 8;
; #pragma unroll
;             EPI_ROWS { const int row = rbase + ai * 128 + m * 16;
; #pragma unroll
;                 for (int bj = 0; bj < 2; ++bj) { const int c = c8 + bj * 128; const u32x4 gw = *(const u32x4*)(P->gates + (long)row * 2048 + goff + c);
;                     f32x4 g0 = {bf_lo(gw.x), bf_hi(gw.x), bf_lo(gw.y), bf_hi(gw.y)}, g1 = {bf_lo(gw.z), bf_hi(gw.z), bf_lo(gw.w), bf_hi(gw.w)};
;                     f32x4 v0 = acc[ai][bj][m][0] * g0, v1 = acc[ai][bj][m][1] * g1;
;                     bf16_t* dst = P->merged + (long)row * 1024 + c;
;                     if (d.epi == E_PROJB) { const u32x4 pw = *(const u32x4*)dst;
;                         v0 += (f32x4){bf_lo(pw.x), bf_hi(pw.x), bf_lo(pw.y), bf_hi(pw.y)}; v1 += (f32x4){bf_lo(pw.z), bf_hi(pw.z), bf_lo(pw.w), bf_hi(pw.w)}; }
;                     store_bf8(dst, v0, v1); } }
.Lproj_a:
	v_mov_b32_e32 v128, v130
	global_load_dwordx4 v[208:211], v128, s[2:3]
	v_mov_b32_e32 v128, v130
	global_load_dwordx4 v[212:215], v128, s[2:3] offset:256
	v_add_u32_e32 v128, 0x10000, v130
	global_load_dwordx4 v[216:219], v128, s[2:3]
	v_add_u32_e32 v128, 0x10000, v130
	global_load_dwordx4 v[220:223], v128, s[2:3] offset:256
	v_add_u32_e32 v128, 0x20000, v130
	global_load_dwordx4 v[224:227], v128, s[2:3]
	v_add_u32_e32 v128, 0x20000, v130
	global_load_dwordx4 v[228:231], v128, s[2:3] offset:256
	v_add_u32_e32 v128, 0x30000, v130
	global_load_dwordx4 v[232:235], v128, s[2:3]
	v_add_u32_e32 v128, 0x30000, v130
	global_load_dwordx4 v[236:239], v128, s[2:3] offset:256
	s_waitcnt vmcnt(7)
	v_lshlrev_b32_e32 v240, 16, v208
	v_and_b32_e32 v241, 0xffff0000, v208
	v_lshlrev_b32_e32 v242, 16, v209
	v_and_b32_e32 v243, 0xffff0000, v209
	v_lshlrev_b32_e32 v244, 16, v210
	v_and_b32_e32 v245, 0xffff0000, v210
	v_lshlrev_b32_e32 v246, 16, v211
	v_and_b32_e32 v247, 0xffff0000, v211
	v_mul_f32_e32 v240, v124, v240
	v_mul_f32_e32 v241, v125, v241
	v_mul_f32_e32 v242, v126, v242
	v_mul_f32_e32 v243, v127, v243
	v_mul_f32_e32 v244, v120, v244
	v_mul_f32_e32 v245, v121, v245
	v_mul_f32_e32 v246, v122, v246
	v_mul_f32_e32 v247, v123, v247
	v_cvt_pk_bf16_f32 v158, v240, v241
	v_cvt_pk_bf16_f32 v159, v242, v243
	v_cvt_pk_bf16_f32 v160, v244, v245
	v_cvt_pk_bf16_f32 v161, v246, v247
	v_mov_b32_e32 v129, v131
	global_store_dwordx4 v129, v[158:161], s[10:11]
	s_waitcnt vmcnt(7)
	v_lshlrev_b32_e32 v240, 16, v212
	v_and_b32_e32 v241, 0xffff0000, v212
	v_lshlrev_b32_e32 v242, 16, v213
	v_and_b32_e32 v243, 0xffff0000, v213
	v_lshlrev_b32_e32 v244, 16, v214
	v_and_b32_e32 v245, 0xffff0000, v214
	v_lshlrev_b32_e32 v246, 16, v215
	v_and_b32_e32 v247, 0xffff0000, v215
	v_mul_f32_e32 v240, v108, v240
	v_mul_f32_e32 v241, v109, v241
	v_mul_f32_e32 v242, v110, v242
	v_mul_f32_e32 v243, v111, v243
	v_mul_f32_e32 v244, v104, v244
	v_mul_f32_e32 v245, v105, v245
	v_mul_f32_e32 v246, v106, v246
	v_mul_f32_e32 v247, v107, v247
	v_cvt_pk_bf16_f32 v166, v240, v241
	v_cvt_pk_bf16_f32 v167, v242, v243
	v_cvt_pk_bf16_f32 v168, v244, v245
	v_cvt_pk_bf16_f32 v169, v246, v247
	v_mov_b32_e32 v129, v131
	global_store_dwordx4 v129, v[166:169], s[10:11] offset:256
	s_waitcnt vmcnt(7)
	v_lshlrev_b32_e32 v240, 16, v216
	v_and_b32_e32 v241, 0xffff0000, v216
	v_lshlrev_b32_e32 v242, 16, v217
	v_and_b32_e32 v243, 0xffff0000, v217
	v_lshlrev_b32_e32 v244, 16, v218
	v_and_b32_e32 v245, 0xffff0000, v218
	v_lshlrev_b32_e32 v246, 16, v219
	v_and_b32_e32 v247, 0xffff0000, v219
	v_mul_f32_e32 v240, v116, v240
	v_mul_f32_e32 v241, v117, v241
	v_mul_f32_e32 v242, v118, v242
	v_mul_f32_e32 v243, v119, v243
	v_mul_f32_e32 v244, v112, v244
	v_mul_f32_e32 v245, v113, v245
	v_mul_f32_e32 v246, v114, v246
	v_mul_f32_e32 v247, v115, v247
	v_cvt_pk_bf16_f32 v158, v240, v241
	v_cvt_pk_bf16_f32 v159, v242, v243
	v_cvt_pk_bf16_f32 v160, v244, v245
	v_cvt_pk_bf16_f32 v161, v246, v247
	v_add_u32_e32 v129, 0x8000, v131
	global_store_dwordx4 v129, v[158:161], s[10:11]
	s_waitcnt vmcnt(7)
	v_lshlrev_b32_e32 v240, 16, v220
	v_and_b32_e32 v241, 0xffff0000, v220
	v_lshlrev_b32_e32 v242, 16, v221
	v_and_b32_e32 v243, 0xffff0000, v221
	v_lshlrev_b32_e32 v244, 16, v222
	v_and_b32_e32 v245, 0xffff0000, v222
	v_lshlrev_b32_e32 v246, 16, v223
	v_and_b32_e32 v247, 0xffff0000, v223
	v_mul_f32_e32 v240, v92, v240
	v_mul_f32_e32 v241, v93, v241
	v_mul_f32_e32 v242, v94, v242
	v_mul_f32_e32 v243, v95, v243
	v_mul_f32_e32 v244, v88, v244
	v_mul_f32_e32 v245, v89, v245
	v_mul_f32_e32 v246, v90, v246
	v_mul_f32_e32 v247, v91, v247
	v_cvt_pk_bf16_f32 v166, v240, v241
	v_cvt_pk_bf16_f32 v167, v242, v243
	v_cvt_pk_bf16_f32 v168, v244, v245
	v_cvt_pk_bf16_f32 v169, v246, v247
	v_add_u32_e32 v129, 0x8000, v131
	global_store_dwordx4 v129, v[166:169], s[10:11] offset:256
	s_waitcnt vmcnt(7)
	v_lshlrev_b32_e32 v240, 16, v224
	v_and_b32_e32 v241, 0xffff0000, v224
	v_lshlrev_b32_e32 v242, 16, v225
	v_and_b32_e32 v243, 0xffff0000, v225
	v_lshlrev_b32_e32 v244, 16, v226
	v_and_b32_e32 v245, 0xffff0000, v226
	v_lshlrev_b32_e32 v246, 16, v227
	v_and_b32_e32 v247, 0xffff0000, v227
	v_mul_f32_e32 v240, v100, v240
	v_mul_f32_e32 v241, v101, v241
	v_mul_f32_e32 v242, v102, v242
	v_mul_f32_e32 v243, v103, v243
	v_mul_f32_e32 v244, v96, v244
	v_mul_f32_e32 v245, v97, v245
	v_mul_f32_e32 v246, v98, v246
	v_mul_f32_e32 v247, v99, v247
	v_cvt_pk_bf16_f32 v158, v240, v241
	v_cvt_pk_bf16_f32 v159, v242, v243
	v_cvt_pk_bf16_f32 v160, v244, v245
	v_cvt_pk_bf16_f32 v161, v246, v247
	v_add_u32_e32 v129, 0x10000, v131
	global_store_dwordx4 v129, v[158:161], s[10:11]
	s_waitcnt vmcnt(7)
	v_lshlrev_b32_e32 v240, 16, v228
	v_and_b32_e32 v241, 0xffff0000, v228
	v_lshlrev_b32_e32 v242, 16, v229
	v_and_b32_e32 v243, 0xffff0000, v229
	v_lshlrev_b32_e32 v244, 16, v230
	v_and_b32_e32 v245, 0xffff0000, v230
	v_lshlrev_b32_e32 v246, 16, v231
	v_and_b32_e32 v247, 0xffff0000, v231
	v_mul_f32_e32 v240, v76, v240
	v_mul_f32_e32 v241, v77, v241
	v_mul_f32_e32 v242, v78, v242
	v_mul_f32_e32 v243, v79, v243
	v_mul_f32_e32 v244, v72, v244
	v_mul_f32_e32 v245, v73, v245
	v_mul_f32_e32 v246, v74, v246
	v_mul_f32_e32 v247, v75, v247
	v_cvt_pk_bf16_f32 v166, v240, v241
	v_cvt_pk_bf16_f32 v167, v242, v243
	v_cvt_pk_bf16_f32 v168, v244, v245
	v_cvt_pk_bf16_f32 v169, v246, v247
	v_add_u32_e32 v129, 0x10000, v131
	global_store_dwordx4 v129, v[166:169], s[10:11] offset:256
	s_waitcnt vmcnt(7)
; DI float bf_lo(unsigned u) { return __uint_as_float(u << 16); }
; DI float bf_hi(unsigned u) { return __uint_as_float(u & 0xffff0000u); }
; #define EPI_ROWS for (int ai = 0; ai < 2; ++ai) for (int m = 0; m < 4; ++m, ({ asm volatile("" ::: "memory"); }))
; DI void store_bf8(bf16_t* p, f32x4 a, f32x4 b) { u32x4 w; w.x = pk2(a[0], a[1]); w.y = pk2(a[2], a[3]); w.z = pk2(b[0], b[1]); w.w = pk2(b[2], b[3]); *(u32x4*)p = w; }
; DI void gemm_run(const GemmDesc& d, char* lds) {
;     ...
;         case E_PROJA: case E_PROJB: {
;             const int goff = d.epi == E_PROJA ? 0 : 1024, c8 = bcol + wc * 32 + fq * 8;
; #pragma unroll
;             EPI_ROWS { const int row = rbase + ai * 128 + m * 16;
; #pragma unroll
;                 for (int bj = 0; bj < 2; ++bj) { const int c = c8 + bj * 128; const u32x4 gw = *(const u32x4*)(P->gates + (long)row * 2048 + goff + c);
;                     f32x4 g0 = {bf_lo(gw.x), bf_hi(gw.x), bf_lo(gw.y), bf_hi(gw.y)}, g1 = {bf_lo(gw.z), bf_hi(gw.z), bf_lo(gw.w), bf_hi(gw.w)};
;                     f32x4 v0 = acc[ai][bj][m][0] * g0, v1 = acc[ai][bj][m][1] * g1;
;                     bf16_t* dst = P->merged + (long)row * 1024 + c;
;                     if (d.epi == E_PROJB) { const u32x4 pw = *(const u32x4*)dst;
;                         v0 += (f32x4){bf_lo(pw.x), bf_hi(pw.x), bf_lo(pw.y), bf_hi(pw.y)}; v1 += (f32x4){bf_lo(pw.z), bf_hi(pw.z), bf_lo(pw.w), bf_hi(pw.w)}; }
;                     store_bf8(dst, v0, v1); } }
	v_lshlrev_b32_e32 v240, 16, v232
	v_and_b32_e32 v241, 0xffff0000, v232
	v_lshlrev_b32_e32 v242, 16, v233
	v_and_b32_e32 v243, 0xffff0000, v233
	v_lshlrev_b32_e32 v244, 16, v234
	v_and_b32_e32 v245, 0xffff0000, v234
	v_lshlrev_b32_e32 v246, 16, v235
	v_and_b32_e32 v247, 0xffff0000, v235
	v_mul_f32_e32 v240, v84, v240
	v_mul_f32_e32 v241, v85, v241
	v_mul_f32_e32 v242, v86, v242
	v_mul_f32_e32 v243, v87, v243
	v_mul_f32_e32 v244, v80, v244
	v_mul_f32_e32 v245, v81, v245
	v_mul_f32_e32 v246, v82, v246
	v_mul_f32_e32 v247, v83, v247
	v_cvt_pk_bf16_f32 v158, v240, v241
	v_cvt_pk_bf16_f32 v159, v242, v243
	v_cvt_pk_bf16_f32 v160, v244, v245
	v_cvt_pk_bf16_f32 v161, v246, v247
	v_add_u32_e32 v129, 0x18000, v131
	global_store_dwordx4 v129, v[158:161], s[10:11]
	s_waitcnt vmcnt(7)
	v_lshlrev_b32_e32 v240, 16, v236
	v_and_b32_e32 v241, 0xffff0000, v236
	v_lshlrev_b32_e32 v242, 16, v237
	v_and_b32_e32 v243, 0xffff0000, v237
	v_lshlrev_b32_e32 v244, 16, v238
	v_and_b32_e32 v245, 0xffff0000, v238
	v_lshlrev_b32_e32 v246, 16, v239
	v_and_b32_e32 v247, 0xffff0000, v239
	v_mul_f32_e32 v240, v68, v240
	v_mul_f32_e32 v241, v69, v241
	v_mul_f32_e32 v242, v70, v242
	v_mul_f32_e32 v243, v71, v243
	v_mul_f32_e32 v244, v64, v244
	v_mul_f32_e32 v245, v65, v245
	v_mul_f32_e32 v246, v66, v246
	v_mul_f32_e32 v247, v67, v247
	v_cvt_pk_bf16_f32 v166, v240, v241
	v_cvt_pk_bf16_f32 v167, v242, v243
	v_cvt_pk_bf16_f32 v168, v244, v245
	v_cvt_pk_bf16_f32 v169, v246, v247
	v_add_u32_e32 v129, 0x18000, v131
	global_store_dwordx4 v129, v[166:169], s[10:11] offset:256
	v_add_u32_e32 v128, 0x80000, v130
	global_load_dwordx4 v[208:211], v128, s[2:3]
	v_add_u32_e32 v128, 0x80000, v130
	global_load_dwordx4 v[212:215], v128, s[2:3] offset:256
	v_add_u32_e32 v128, 0x90000, v130
	global_load_dwordx4 v[216:219], v128, s[2:3]
	v_add_u32_e32 v128, 0x90000, v130
	global_load_dwordx4 v[220:223], v128, s[2:3] offset:256
	v_add_u32_e32 v128, 0xa0000, v130
	global_load_dwordx4 v[224:227], v128, s[2:3]
	v_add_u32_e32 v128, 0xa0000, v130
	global_load_dwordx4 v[228:231], v128, s[2:3] offset:256
	v_add_u32_e32 v128, 0xb0000, v130
	global_load_dwordx4 v[232:235], v128, s[2:3]
	v_add_u32_e32 v128, 0xb0000, v130
	global_load_dwordx4 v[236:239], v128, s[2:3] offset:256
	s_waitcnt vmcnt(7)
	v_lshlrev_b32_e32 v240, 16, v208
	v_and_b32_e32 v241, 0xffff0000, v208
	v_lshlrev_b32_e32 v242, 16, v209
	v_and_b32_e32 v243, 0xffff0000, v209
	v_lshlrev_b32_e32 v244, 16, v210
	v_and_b32_e32 v245, 0xffff0000, v210
	v_lshlrev_b32_e32 v246, 16, v211
	v_and_b32_e32 v247, 0xffff0000, v211
	v_mul_f32_e32 v240, v60, v240
	v_mul_f32_e32 v241, v61, v241
	v_mul_f32_e32 v242, v62, v242
	v_mul_f32_e32 v243, v63, v243
	v_mul_f32_e32 v244, v56, v244
	v_mul_f32_e32 v245, v57, v245
	v_mul_f32_e32 v246, v58, v246
	v_mul_f32_e32 v247, v59, v247
	v_cvt_pk_bf16_f32 v158, v240, v241
	v_cvt_pk_bf16_f32 v159, v242, v243
	v_cvt_pk_bf16_f32 v160, v244, v245
	v_cvt_pk_bf16_f32 v161, v246, v247
	v_add_u32_e32 v129, 0x40000, v131
	global_store_dwordx4 v129, v[158:161], s[10:11]
	s_waitcnt vmcnt(7)
	v_lshlrev_b32_e32 v240, 16, v212
	v_and_b32_e32 v241, 0xffff0000, v212
	v_lshlrev_b32_e32 v242, 16, v213
	v_and_b32_e32 v243, 0xffff0000, v213
	v_lshlrev_b32_e32 v244, 16, v214
	v_and_b32_e32 v245, 0xffff0000, v214
	v_lshlrev_b32_e32 v246, 16, v215
	v_and_b32_e32 v247, 0xffff0000, v215
	v_mul_f32_e32 v240, v44, v240
	v_mul_f32_e32 v241, v45, v241
	v_mul_f32_e32 v242, v46, v242
	v_mul_f32_e32 v243, v47, v243
	v_mul_f32_e32 v244, v40, v244
	v_mul_f32_e32 v245, v41, v245
	v_mul_f32_e32 v246, v42, v246
	v_mul_f32_e32 v247, v43, v247
	v_cvt_pk_bf16_f32 v166, v240, v241
	v_cvt_pk_bf16_f32 v167, v242, v243
	v_cvt_pk_bf16_f32 v168, v244, v245
	v_cvt_pk_bf16_f32 v169, v246, v247
	v_add_u32_e32 v129, 0x40000, v131
	global_store_dwordx4 v129, v[166:169], s[10:11] offset:256
	s_waitcnt vmcnt(7)
	v_lshlrev_b32_e32 v240, 16, v216
	v_and_b32_e32 v241, 0xffff0000, v216
	v_lshlrev_b32_e32 v242, 16, v217
	v_and_b32_e32 v243, 0xffff0000, v217
	v_lshlrev_b32_e32 v244, 16, v218
	v_and_b32_e32 v245, 0xffff0000, v218
	v_lshlrev_b32_e32 v246, 16, v219
	v_and_b32_e32 v247, 0xffff0000, v219
	v_mul_f32_e32 v240, v52, v240
	v_mul_f32_e32 v241, v53, v241
	v_mul_f32_e32 v242, v54, v242
	v_mul_f32_e32 v243, v55, v243
	v_mul_f32_e32 v244, v48, v244
	v_mul_f32_e32 v245, v49, v245
	v_mul_f32_e32 v246, v50, v246
	v_mul_f32_e32 v247, v51, v247
	v_cvt_pk_bf16_f32 v158, v240, v241
	v_cvt_pk_bf16_f32 v159, v242, v243
	v_cvt_pk_bf16_f32 v160, v244, v245
	v_cvt_pk_bf16_f32 v161, v246, v247
	v_add_u32_e32 v129, 0x48000, v131
	global_store_dwordx4 v129, v[158:161], s[10:11]
	s_waitcnt vmcnt(7)
; DI float bf_lo(unsigned u) { return __uint_as_float(u << 16); }
; DI float bf_hi(unsigned u) { return __uint_as_float(u & 0xffff0000u); }
; #define EPI_ROWS for (int ai = 0; ai < 2; ++ai) for (int m = 0; m < 4; ++m, ({ asm volatile("" ::: "memory"); }))
; DI void store_bf8(bf16_t* p, f32x4 a, f32x4 b) { u32x4 w; w.x = pk2(a[0], a[1]); w.y = pk2(a[2], a[3]); w.z = pk2(b[0], b[1]); w.w = pk2(b[2], b[3]); *(u32x4*)p = w; }
; DI void gemm_run(const GemmDesc& d, char* lds) {
;     ...
;         case E_PROJA: case E_PROJB: {
;             const int goff = d.epi == E_PROJA ? 0 : 1024, c8 = bcol + wc * 32 + fq * 8;
; #pragma unroll
;             EPI_ROWS { const int row = rbase + ai * 128 + m * 16;
; #pragma unroll
;                 for (int bj = 0; bj < 2; ++bj) { const int c = c8 + bj * 128; const u32x4 gw = *(const u32x4*)(P->gates + (long)row * 2048 + goff + c);
;                     f32x4 g0 = {bf_lo(gw.x), bf_hi(gw.x), bf_lo(gw.y), bf_hi(gw.y)}, g1 = {bf_lo(gw.z), bf_hi(gw.z), bf_lo(gw.w), bf_hi(gw.w)};
;                     f32x4 v0 = acc[ai][bj][m][0] * g0, v1 = acc[ai][bj][m][1] * g1;
;                     bf16_t* dst = P->merged + (long)row * 1024 + c;
;                     if (d.epi == E_PROJB) { const u32x4 pw = *(const u32x4*)dst;
;                         v0 += (f32x4){bf_lo(pw.x), bf_hi(pw.x), bf_lo(pw.y), bf_hi(pw.y)}; v1 += (f32x4){bf_lo(pw.z), bf_hi(pw.z), bf_lo(pw.w), bf_hi(pw.w)}; }
;                     store_bf8(dst, v0, v1); } }
	v_lshlrev_b32_e32 v240, 16, v220
	v_and_b32_e32 v241, 0xffff0000, v220
	v_lshlrev_b32_e32 v242, 16, v221
	v_and_b32_e32 v243, 0xffff0000, v221
	v_lshlrev_b32_e32 v244, 16, v222
	v_and_b32_e32 v245, 0xffff0000, v222
	v_lshlrev_b32_e32 v246, 16, v223
	v_and_b32_e32 v247, 0xffff0000, v223
	v_mul_f32_e32 v240, v28, v240
	v_mul_f32_e32 v241, v29, v241
	v_mul_f32_e32 v242, v30, v242
	v_mul_f32_e32 v243, v31, v243
	v_mul_f32_e32 v244, v24, v244
	v_mul_f32_e32 v245, v25, v245
	v_mul_f32_e32 v246, v26, v246
	v_mul_f32_e32 v247, v27, v247
	v_cvt_pk_bf16_f32 v166, v240, v241
	v_cvt_pk_bf16_f32 v167, v242, v243
	v_cvt_pk_bf16_f32 v168, v244, v245
	v_cvt_pk_bf16_f32 v169, v246, v247
	v_add_u32_e32 v129, 0x48000, v131
	global_store_dwordx4 v129, v[166:169], s[10:11] offset:256
	s_waitcnt vmcnt(7)
	v_lshlrev_b32_e32 v240, 16, v224
	v_and_b32_e32 v241, 0xffff0000, v224
	v_lshlrev_b32_e32 v242, 16, v225
	v_and_b32_e32 v243, 0xffff0000, v225
	v_lshlrev_b32_e32 v244, 16, v226
	v_and_b32_e32 v245, 0xffff0000, v226
	v_lshlrev_b32_e32 v246, 16, v227
	v_and_b32_e32 v247, 0xffff0000, v227
	v_mul_f32_e32 v240, v36, v240
	v_mul_f32_e32 v241, v37, v241
	v_mul_f32_e32 v242, v38, v242
	v_mul_f32_e32 v243, v39, v243
	v_mul_f32_e32 v244, v32, v244
	v_mul_f32_e32 v245, v33, v245
	v_mul_f32_e32 v246, v34, v246
	v_mul_f32_e32 v247, v35, v247
	v_cvt_pk_bf16_f32 v158, v240, v241
	v_cvt_pk_bf16_f32 v159, v242, v243
	v_cvt_pk_bf16_f32 v160, v244, v245
	v_cvt_pk_bf16_f32 v161, v246, v247
	v_add_u32_e32 v129, 0x50000, v131
	global_store_dwordx4 v129, v[158:161], s[10:11]
	s_waitcnt vmcnt(7)
	v_lshlrev_b32_e32 v240, 16, v228
	v_and_b32_e32 v241, 0xffff0000, v228
	v_lshlrev_b32_e32 v242, 16, v229
	v_and_b32_e32 v243, 0xffff0000, v229
	v_lshlrev_b32_e32 v244, 16, v230
	v_and_b32_e32 v245, 0xffff0000, v230
	v_lshlrev_b32_e32 v246, 16, v231
	v_and_b32_e32 v247, 0xffff0000, v231
	v_mul_f32_e32 v240, v12, v240
	v_mul_f32_e32 v241, v13, v241
	v_mul_f32_e32 v242, v14, v242
	v_mul_f32_e32 v243, v15, v243
	v_mul_f32_e32 v244, v8, v244
	v_mul_f32_e32 v245, v9, v245
	v_mul_f32_e32 v246, v10, v246
	v_mul_f32_e32 v247, v11, v247
	v_cvt_pk_bf16_f32 v166, v240, v241
	v_cvt_pk_bf16_f32 v167, v242, v243
	v_cvt_pk_bf16_f32 v168, v244, v245
	v_cvt_pk_bf16_f32 v169, v246, v247
	v_add_u32_e32 v129, 0x50000, v131
	global_store_dwordx4 v129, v[166:169], s[10:11] offset:256
	s_waitcnt vmcnt(7)
	v_lshlrev_b32_e32 v240, 16, v232
	v_and_b32_e32 v241, 0xffff0000, v232
	v_lshlrev_b32_e32 v242, 16, v233
	v_and_b32_e32 v243, 0xffff0000, v233
	v_lshlrev_b32_e32 v244, 16, v234
	v_and_b32_e32 v245, 0xffff0000, v234
	v_lshlrev_b32_e32 v246, 16, v235
	v_and_b32_e32 v247, 0xffff0000, v235
	v_mul_f32_e32 v240, v20, v240
	v_mul_f32_e32 v241, v21, v241
	v_mul_f32_e32 v242, v22, v242
	v_mul_f32_e32 v243, v23, v243
	v_mul_f32_e32 v244, v16, v244
	v_mul_f32_e32 v245, v17, v245
	v_mul_f32_e32 v246, v18, v246
	v_mul_f32_e32 v247, v19, v247
	v_cvt_pk_bf16_f32 v158, v240, v241
	v_cvt_pk_bf16_f32 v159, v242, v243
	v_cvt_pk_bf16_f32 v160, v244, v245
	v_cvt_pk_bf16_f32 v161, v246, v247
	v_add_u32_e32 v129, 0x58000, v131
	global_store_dwordx4 v129, v[158:161], s[10:11]
	s_waitcnt vmcnt(7)
	v_lshlrev_b32_e32 v240, 16, v236
	v_and_b32_e32 v241, 0xffff0000, v236
	v_lshlrev_b32_e32 v242, 16, v237
	v_and_b32_e32 v243, 0xffff0000, v237
	v_lshlrev_b32_e32 v244, 16, v238
	v_and_b32_e32 v245, 0xffff0000, v238
	v_lshlrev_b32_e32 v246, 16, v239
	v_and_b32_e32 v247, 0xffff0000, v239
	v_mul_f32_e32 v240, v4, v240
	v_mul_f32_e32 v241, v5, v241
	v_mul_f32_e32 v242, v6, v242
	v_mul_f32_e32 v243, v7, v243
	v_mul_f32_e32 v244, v0, v244
	v_mul_f32_e32 v245, v1, v245
	v_mul_f32_e32 v246, v2, v246
	v_mul_f32_e32 v247, v3, v247
	v_cvt_pk_bf16_f32 v166, v240, v241
	v_cvt_pk_bf16_f32 v167, v242, v243
	v_cvt_pk_bf16_f32 v168, v244, v245
	v_cvt_pk_bf16_f32 v169, v246, v247
	v_add_u32_e32 v129, 0x58000, v131
	global_store_dwordx4 v129, v[166:169], s[10:11] offset:256
